# GEMM-out epilogue fused with norm2 (fuse2) + hgrn_pass_c S-transpose items remapped for LDS banks (smapd)
# speedup vs baseline: 1.1773x; 1.0145x over previous
.LBB0_1116:
	v_and_b32_e32 v41, 63, v30
	v_lshrrev_b32_e32 v171, 6, v30
	v_and_b32_e32 v188, 1, v41
	v_lshrrev_b32_e32 v189, 5, v41
	v_lshl_or_b32 v188, v189, 1, v188
	v_bfe_u32 v189, v41, 1, 4
	v_lshlrev_b32_e32 v0, 9, v189
	v_lshl_add_u32 v0, v188, 4, v0
	v_lshl_add_u32 v0, v171, 6, v0
	s_mov_b64 s[24:25], s[88:89]
	global_load_dwordx4 v[2:5], v0, s[24:25]
	s_add_u32 s24, s24, 0x2000
	s_addc_u32 s25, s25, 0
	global_load_dwordx4 v[6:9], v0, s[24:25]
	s_add_u32 s24, s24, 0x2000
	s_addc_u32 s25, s25, 0
	global_load_dwordx4 v[10:13], v0, s[24:25]
	s_add_u32 s24, s24, 0x2000
	s_addc_u32 s25, s25, 0
	global_load_dwordx4 v[14:17], v0, s[24:25]
	s_add_u32 s24, s24, 0x2000
	s_addc_u32 s25, s25, 0
	global_load_dwordx4 v[18:21], v0, s[24:25]
	s_add_u32 s24, s24, 0x2000
	s_addc_u32 s25, s25, 0
	global_load_dwordx4 v[22:25], v0, s[24:25]
	s_add_u32 s24, s24, 0x2000
	s_addc_u32 s25, s25, 0
	global_load_dwordx4 v[172:175], v0, s[24:25]
	s_add_u32 s24, s24, 0x2000
	s_addc_u32 s25, s25, 0
	global_load_dwordx4 v[26:29], v0, s[24:25]
	v_lshl_add_u32 v171, v171, 2, v188
	v_mul_u32_u24_e32 v171, 0x440, v171
	v_lshl_add_u32 v171, v189, 1, v171
	v_add_u32_e32 v171, s97, v171
	s_waitcnt vmcnt(7)
	v_cvt_pk_bf16_f32 v2, v2, v3
	v_cvt_pk_bf16_f32 v4, v4, v5
	ds_write_b16 v171, v2
	ds_write_b16_d16_hi v171, v2 offset:272
	ds_write_b16 v171, v4 offset:544
	ds_write_b16_d16_hi v171, v4 offset:816
	s_waitcnt vmcnt(6)
	v_cvt_pk_bf16_f32 v6, v6, v7
	v_cvt_pk_bf16_f32 v8, v8, v9
	ds_write_b16 v171, v6 offset:32
	ds_write_b16_d16_hi v171, v6 offset:304
	ds_write_b16 v171, v8 offset:576
	ds_write_b16_d16_hi v171, v8 offset:848
	s_waitcnt vmcnt(5)
	v_cvt_pk_bf16_f32 v10, v10, v11
	v_cvt_pk_bf16_f32 v12, v12, v13
	ds_write_b16 v171, v10 offset:64
	ds_write_b16_d16_hi v171, v10 offset:336
	ds_write_b16 v171, v12 offset:608
	ds_write_b16_d16_hi v171, v12 offset:880
	s_waitcnt vmcnt(4)
	v_cvt_pk_bf16_f32 v14, v14, v15
	v_cvt_pk_bf16_f32 v16, v16, v17
	ds_write_b16 v171, v14 offset:96
	ds_write_b16_d16_hi v171, v14 offset:368
	ds_write_b16 v171, v16 offset:640
	ds_write_b16_d16_hi v171, v16 offset:912
	s_waitcnt vmcnt(3)
	v_cvt_pk_bf16_f32 v18, v18, v19
	v_cvt_pk_bf16_f32 v20, v20, v21
	ds_write_b16 v171, v18 offset:128
	ds_write_b16_d16_hi v171, v18 offset:400
	ds_write_b16 v171, v20 offset:672
	ds_write_b16_d16_hi v171, v20 offset:944
	s_waitcnt vmcnt(2)
	v_cvt_pk_bf16_f32 v22, v22, v23
	v_cvt_pk_bf16_f32 v24, v24, v25
	ds_write_b16 v171, v22 offset:160
	ds_write_b16_d16_hi v171, v22 offset:432
	ds_write_b16 v171, v24 offset:704
	ds_write_b16_d16_hi v171, v24 offset:976
	s_waitcnt vmcnt(1)
	v_cvt_pk_bf16_f32 v172, v172, v173
	v_cvt_pk_bf16_f32 v174, v174, v175
	ds_write_b16 v171, v172 offset:192
	ds_write_b16_d16_hi v171, v172 offset:464
	ds_write_b16 v171, v174 offset:736
	ds_write_b16_d16_hi v171, v174 offset:1008
	s_waitcnt vmcnt(0)
	v_cvt_pk_bf16_f32 v26, v26, v27
	v_cvt_pk_bf16_f32 v28, v28, v29
	ds_write_b16 v171, v26 offset:224
	ds_write_b16_d16_hi v171, v26 offset:496
	ds_write_b16 v171, v28 offset:768
	ds_write_b16_d16_hi v171, v28 offset:1040

.Lf2_start:
	s_waitcnt vmcnt(0) lgkmcnt(0)
	v_lshrrev_b32_e32 v232, 6, v177
	v_and_b32_e32 v233, 63, v177
	v_readfirstlane_b32 s8, v232
	v_readlane_b32 s40, v255, 4
	v_readlane_b32 s41, v255, 5
	v_readlane_b32 s44, v253, 1
	v_readlane_b32 s45, v253, 2
	v_readlane_b32 s56, v252, 51
	v_readlane_b32 s57, v252, 52
	v_readlane_b32 s46, v252, 2
	v_readlane_b32 s47, v252, 3
	v_readlane_b32 s0, v252, 4
	v_readlane_b32 s1, v252, 5
	s_nop 3
	s_cmp_gt_u32 s8, 3
	s_cbranch_scc1 .Lf2_nosync
	s_barrier
.Lf2_nosync:
	s_barrier
	s_and_b32 s9, s72, 7
	s_lshl_b32 s9, s9, 3
	s_bfe_u32 s11, s72, 0x30003
	s_or_b32 s9, s9, s11
	s_lshr_b32 s10, s72, 6
	v_and_b32_e32 v234, 15, v233
	v_lshrrev_b32_e32 v235, 4, v233
	s_and_b32 s11, s8, 3
	s_lshr_b32 s12, s8, 2
	s_lshl_b32 s12, s12, 6
	v_add_u32_e32 v236, s12, v234
	s_lshl_b32 s12, s11, 5
	v_lshl_add_u32 v237, v235, 2, s12
	v_lshl_add_u32 v230, v236, 4, v235
	s_lshl_b32 s12, s11, 2
	v_add_u32_e32 v230, s12, v230
	v_lshlrev_b32_e32 v230, 2, v230
	s_lshl_b32 s12, s10, 8
	v_add_u32_e32 v229, s12, v237
	v_lshlrev_b32_e32 v229, 2, v229
	s_lshl_b32 s12, s9, 8
	v_add_u32_e32 v228, s12, v236
	v_lshl_add_u32 v228, v228, 12, v229
	v_lshrrev_b32_e32 v231, 1, v228
	s_sub_u32 s0, s0, 0x2000000
	s_subb_u32 s1, s1, 0
	s_cmp_lt_u32 s9, 32
	s_cselect_b32 s46, s46, s0
	s_cselect_b32 s47, s47, s1
	s_sub_u32 s11, s9, 32
	s_lshr_b32 s11, s11, 4
	s_add_u32 s11, s11, 1
	s_cmp_lt_u32 s9, 32
	s_cselect_b32 s11, 0, s11
	s_mul_i32 s11, s11, 0x6000
	s_add_u32 s11, s40, s11
	s_addc_u32 s12, s41, 0
	s_add_u32 s48, s11, 0x2000
	s_addc_u32 s49, s12, 0
	s_add_u32 s60, s11, 0x3000
	s_addc_u32 s61, s12, 0
	s_add_u32 s58, s11, 0x4000
	s_addc_u32 s59, s12, 0
	s_add_u32 s52, s40, 0xf984000
	s_addc_u32 s53, s41, 0
	s_add_u32 s54, s40, 0x1380000
	s_addc_u32 s55, s41, 0
	global_load_dwordx4 v[144:147], v229, s[48:49]
	global_load_dwordx4 v[148:151], v229, s[48:49] offset:64
	global_load_dwordx4 v[152:155], v229, s[48:49] offset:512
	global_load_dwordx4 v[156:159], v229, s[48:49] offset:576
	global_load_dwordx4 v[160:163], v229, s[56:57]
	global_load_dwordx4 v[164:167], v229, s[56:57] offset:64
	global_load_dwordx4 v[168:171], v229, s[56:57] offset:512
	global_load_dwordx4 v[172:175], v229, s[56:57] offset:576
	global_load_dwordx4 v[80:83], v229, s[58:59]
	global_load_dwordx4 v[84:87], v229, s[58:59] offset:64
	global_load_dwordx4 v[88:91], v229, s[58:59] offset:512
	global_load_dwordx4 v[92:95], v229, s[58:59] offset:576
	s_add_u32 s50, s46, 0x0
	s_addc_u32 s51, s47, 0
	global_load_dwordx4 v[180:183], v228, s[50:51]
	global_load_dwordx4 v[184:187], v228, s[50:51] offset:64
	global_load_dwordx4 v[188:191], v228, s[50:51] offset:512
	global_load_dwordx4 v[192:195], v228, s[50:51] offset:576
	s_add_u32 s50, s46, 0x10000
	s_addc_u32 s51, s47, 0
	global_load_dwordx4 v[196:199], v228, s[50:51]
	global_load_dwordx4 v[200:203], v228, s[50:51] offset:64
	global_load_dwordx4 v[204:207], v228, s[50:51] offset:512
	global_load_dwordx4 v[208:211], v228, s[50:51] offset:576
	s_waitcnt vmcnt(4)
	v_pk_add_f32 v[80:81], v[80:81], 1.0 op_sel_hi:[1,0]
	v_pk_add_f32 v[82:83], v[82:83], 1.0 op_sel_hi:[1,0]
	v_pk_add_f32 v[84:85], v[84:85], 1.0 op_sel_hi:[1,0]
	v_pk_add_f32 v[86:87], v[86:87], 1.0 op_sel_hi:[1,0]
	v_pk_add_f32 v[88:89], v[88:89], 1.0 op_sel_hi:[1,0]
	v_pk_add_f32 v[90:91], v[90:91], 1.0 op_sel_hi:[1,0]
	v_pk_add_f32 v[92:93], v[92:93], 1.0 op_sel_hi:[1,0]
	v_pk_add_f32 v[94:95], v[94:95], 1.0 op_sel_hi:[1,0]
	v_pk_fma_f32 v[140:141], v[140:141], v[144:145], v[180:181]
	v_pk_fma_f32 v[142:143], v[142:143], v[146:147], v[182:183]
	v_pk_fma_f32 v[136:137], v[136:137], v[148:149], v[184:185]
	v_pk_fma_f32 v[138:139], v[138:139], v[150:151], v[186:187]
	v_pk_fma_f32 v[132:133], v[132:133], v[152:153], v[188:189]
	v_pk_fma_f32 v[134:135], v[134:135], v[154:155], v[190:191]
	v_pk_fma_f32 v[128:129], v[128:129], v[156:157], v[192:193]
	v_pk_fma_f32 v[130:131], v[130:131], v[158:159], v[194:195]
	s_add_u32 s62, s44, 0x0
	s_addc_u32 s63, s45, 0
	global_store_dwordx4 v228, v[140:143], s[62:63] sc1
	global_store_dwordx4 v228, v[136:139], s[62:63] offset:64 sc1
	global_store_dwordx4 v228, v[132:135], s[62:63] offset:512 sc1
	global_store_dwordx4 v228, v[128:131], s[62:63] offset:576 sc1
	v_mul_f32_e32 v232, v140, v140
	v_fmac_f32_e32 v232, v141, v141
	v_fmac_f32_e32 v232, v142, v142
	v_fmac_f32_e32 v232, v143, v143
	v_fmac_f32_e32 v232, v136, v136
	v_fmac_f32_e32 v232, v137, v137
	v_fmac_f32_e32 v232, v138, v138
	v_fmac_f32_e32 v232, v139, v139
	v_fmac_f32_e32 v232, v132, v132
	v_fmac_f32_e32 v232, v133, v133
	v_fmac_f32_e32 v232, v134, v134
	v_fmac_f32_e32 v232, v135, v135
	v_fmac_f32_e32 v232, v128, v128
	v_fmac_f32_e32 v232, v129, v129
	v_fmac_f32_e32 v232, v130, v130
	v_fmac_f32_e32 v232, v131, v131
	ds_write_b32 v230, v232 offset:0
	s_add_u32 s50, s46, 0x20000
	s_addc_u32 s51, s47, 0
	global_load_dwordx4 v[180:183], v228, s[50:51]
	global_load_dwordx4 v[184:187], v228, s[50:51] offset:64
	global_load_dwordx4 v[188:191], v228, s[50:51] offset:512
	global_load_dwordx4 v[192:195], v228, s[50:51] offset:576
	s_waitcnt vmcnt(8)
	v_pk_fma_f32 v[124:125], v[124:125], v[144:145], v[196:197]
	v_pk_fma_f32 v[126:127], v[126:127], v[146:147], v[198:199]
	v_pk_fma_f32 v[120:121], v[120:121], v[148:149], v[200:201]
	v_pk_fma_f32 v[122:123], v[122:123], v[150:151], v[202:203]
	v_pk_fma_f32 v[116:117], v[116:117], v[152:153], v[204:205]
	v_pk_fma_f32 v[118:119], v[118:119], v[154:155], v[206:207]
	v_pk_fma_f32 v[112:113], v[112:113], v[156:157], v[208:209]
	v_pk_fma_f32 v[114:115], v[114:115], v[158:159], v[210:211]
	s_add_u32 s62, s44, 0x10000
	s_addc_u32 s63, s45, 0
	global_store_dwordx4 v228, v[124:127], s[62:63] sc1
	global_store_dwordx4 v228, v[120:123], s[62:63] offset:64 sc1
	global_store_dwordx4 v228, v[116:119], s[62:63] offset:512 sc1
	global_store_dwordx4 v228, v[112:115], s[62:63] offset:576 sc1
	v_mul_f32_e32 v232, v124, v124
	v_fmac_f32_e32 v232, v125, v125
	v_fmac_f32_e32 v232, v126, v126
	v_fmac_f32_e32 v232, v127, v127
	v_fmac_f32_e32 v232, v120, v120
	v_fmac_f32_e32 v232, v121, v121
	v_fmac_f32_e32 v232, v122, v122
	v_fmac_f32_e32 v232, v123, v123
	v_fmac_f32_e32 v232, v116, v116
	v_fmac_f32_e32 v232, v117, v117
	v_fmac_f32_e32 v232, v118, v118
	v_fmac_f32_e32 v232, v119, v119
	v_fmac_f32_e32 v232, v112, v112
	v_fmac_f32_e32 v232, v113, v113
	v_fmac_f32_e32 v232, v114, v114
	v_fmac_f32_e32 v232, v115, v115
	ds_write_b32 v230, v232 offset:1024
	s_add_u32 s50, s46, 0x30000
	s_addc_u32 s51, s47, 0
	global_load_dwordx4 v[196:199], v228, s[50:51]
	global_load_dwordx4 v[200:203], v228, s[50:51] offset:64
	global_load_dwordx4 v[204:207], v228, s[50:51] offset:512
	global_load_dwordx4 v[208:211], v228, s[50:51] offset:576
	s_waitcnt vmcnt(8)
	v_pk_fma_f32 v[108:109], v[108:109], v[144:145], v[180:181]
	v_pk_fma_f32 v[110:111], v[110:111], v[146:147], v[182:183]
	v_pk_fma_f32 v[104:105], v[104:105], v[148:149], v[184:185]
	v_pk_fma_f32 v[106:107], v[106:107], v[150:151], v[186:187]
	v_pk_fma_f32 v[100:101], v[100:101], v[152:153], v[188:189]
	v_pk_fma_f32 v[102:103], v[102:103], v[154:155], v[190:191]
	v_pk_fma_f32 v[96:97], v[96:97], v[156:157], v[192:193]
	v_pk_fma_f32 v[98:99], v[98:99], v[158:159], v[194:195]
	s_add_u32 s62, s44, 0x20000
	s_addc_u32 s63, s45, 0
	global_store_dwordx4 v228, v[108:111], s[62:63] sc1
	global_store_dwordx4 v228, v[104:107], s[62:63] offset:64 sc1
	global_store_dwordx4 v228, v[100:103], s[62:63] offset:512 sc1
	global_store_dwordx4 v228, v[96:99], s[62:63] offset:576 sc1
	v_mul_f32_e32 v232, v108, v108
	v_fmac_f32_e32 v232, v109, v109
	v_fmac_f32_e32 v232, v110, v110
	v_fmac_f32_e32 v232, v111, v111
	v_fmac_f32_e32 v232, v104, v104
	v_fmac_f32_e32 v232, v105, v105
	v_fmac_f32_e32 v232, v106, v106
	v_fmac_f32_e32 v232, v107, v107
	v_fmac_f32_e32 v232, v100, v100
	v_fmac_f32_e32 v232, v101, v101
	v_fmac_f32_e32 v232, v102, v102
	v_fmac_f32_e32 v232, v103, v103
	v_fmac_f32_e32 v232, v96, v96
	v_fmac_f32_e32 v232, v97, v97
	v_fmac_f32_e32 v232, v98, v98
	v_fmac_f32_e32 v232, v99, v99
	ds_write_b32 v230, v232 offset:2048
	s_add_u32 s50, s46, 0x80000
	s_addc_u32 s51, s47, 0
	global_load_dwordx4 v[180:183], v228, s[50:51]
	global_load_dwordx4 v[184:187], v228, s[50:51] offset:64
	global_load_dwordx4 v[188:191], v228, s[50:51] offset:512
	global_load_dwordx4 v[192:195], v228, s[50:51] offset:576
	s_waitcnt vmcnt(8)
	v_pk_fma_f32 v[76:77], v[76:77], v[144:145], v[196:197]
	v_pk_fma_f32 v[78:79], v[78:79], v[146:147], v[198:199]
	v_pk_fma_f32 v[72:73], v[72:73], v[148:149], v[200:201]
	v_pk_fma_f32 v[74:75], v[74:75], v[150:151], v[202:203]
	v_pk_fma_f32 v[68:69], v[68:69], v[152:153], v[204:205]
	v_pk_fma_f32 v[70:71], v[70:71], v[154:155], v[206:207]
	v_pk_fma_f32 v[64:65], v[64:65], v[156:157], v[208:209]
	v_pk_fma_f32 v[66:67], v[66:67], v[158:159], v[210:211]
	s_add_u32 s62, s44, 0x30000
	s_addc_u32 s63, s45, 0
	global_store_dwordx4 v228, v[76:79], s[62:63] sc1
	global_store_dwordx4 v228, v[72:75], s[62:63] offset:64 sc1
	global_store_dwordx4 v228, v[68:71], s[62:63] offset:512 sc1
	global_store_dwordx4 v228, v[64:67], s[62:63] offset:576 sc1
	v_mul_f32_e32 v232, v76, v76
	v_fmac_f32_e32 v232, v77, v77
	v_fmac_f32_e32 v232, v78, v78
	v_fmac_f32_e32 v232, v79, v79
	v_fmac_f32_e32 v232, v72, v72
	v_fmac_f32_e32 v232, v73, v73
	v_fmac_f32_e32 v232, v74, v74
	v_fmac_f32_e32 v232, v75, v75
	v_fmac_f32_e32 v232, v68, v68
	v_fmac_f32_e32 v232, v69, v69
	v_fmac_f32_e32 v232, v70, v70
	v_fmac_f32_e32 v232, v71, v71
	v_fmac_f32_e32 v232, v64, v64
	v_fmac_f32_e32 v232, v65, v65
	v_fmac_f32_e32 v232, v66, v66
	v_fmac_f32_e32 v232, v67, v67
	ds_write_b32 v230, v232 offset:3072
	s_add_u32 s50, s46, 0x90000
	s_addc_u32 s51, s47, 0
	global_load_dwordx4 v[196:199], v228, s[50:51]
	global_load_dwordx4 v[200:203], v228, s[50:51] offset:64
	global_load_dwordx4 v[204:207], v228, s[50:51] offset:512
	global_load_dwordx4 v[208:211], v228, s[50:51] offset:576
	s_waitcnt vmcnt(8)
	v_pk_fma_f32 v[60:61], v[60:61], v[144:145], v[180:181]
	v_pk_fma_f32 v[62:63], v[62:63], v[146:147], v[182:183]
	v_pk_fma_f32 v[56:57], v[56:57], v[148:149], v[184:185]
	v_pk_fma_f32 v[58:59], v[58:59], v[150:151], v[186:187]
	v_pk_fma_f32 v[52:53], v[52:53], v[152:153], v[188:189]
	v_pk_fma_f32 v[54:55], v[54:55], v[154:155], v[190:191]
	v_pk_fma_f32 v[48:49], v[48:49], v[156:157], v[192:193]
	v_pk_fma_f32 v[50:51], v[50:51], v[158:159], v[194:195]
	s_add_u32 s62, s44, 0x80000
	s_addc_u32 s63, s45, 0
	global_store_dwordx4 v228, v[60:63], s[62:63] sc1
	global_store_dwordx4 v228, v[56:59], s[62:63] offset:64 sc1
	global_store_dwordx4 v228, v[52:55], s[62:63] offset:512 sc1
	global_store_dwordx4 v228, v[48:51], s[62:63] offset:576 sc1
	v_mul_f32_e32 v232, v60, v60
	v_fmac_f32_e32 v232, v61, v61
	v_fmac_f32_e32 v232, v62, v62
	v_fmac_f32_e32 v232, v63, v63
	v_fmac_f32_e32 v232, v56, v56
	v_fmac_f32_e32 v232, v57, v57
	v_fmac_f32_e32 v232, v58, v58
	v_fmac_f32_e32 v232, v59, v59
	v_fmac_f32_e32 v232, v52, v52
	v_fmac_f32_e32 v232, v53, v53
	v_fmac_f32_e32 v232, v54, v54
	v_fmac_f32_e32 v232, v55, v55
	v_fmac_f32_e32 v232, v48, v48
	v_fmac_f32_e32 v232, v49, v49
	v_fmac_f32_e32 v232, v50, v50
	v_fmac_f32_e32 v232, v51, v51
	ds_write_b32 v230, v232 offset:8192
	s_add_u32 s50, s46, 0xa0000
	s_addc_u32 s51, s47, 0
	global_load_dwordx4 v[180:183], v228, s[50:51]
	global_load_dwordx4 v[184:187], v228, s[50:51] offset:64
	global_load_dwordx4 v[188:191], v228, s[50:51] offset:512
	global_load_dwordx4 v[192:195], v228, s[50:51] offset:576
	s_waitcnt vmcnt(8)
	v_pk_fma_f32 v[44:45], v[44:45], v[144:145], v[196:197]
	v_pk_fma_f32 v[46:47], v[46:47], v[146:147], v[198:199]
	v_pk_fma_f32 v[40:41], v[40:41], v[148:149], v[200:201]
	v_pk_fma_f32 v[42:43], v[42:43], v[150:151], v[202:203]
	v_pk_fma_f32 v[36:37], v[36:37], v[152:153], v[204:205]
	v_pk_fma_f32 v[38:39], v[38:39], v[154:155], v[206:207]
	v_pk_fma_f32 v[32:33], v[32:33], v[156:157], v[208:209]
	v_pk_fma_f32 v[34:35], v[34:35], v[158:159], v[210:211]
	s_add_u32 s62, s44, 0x90000
	s_addc_u32 s63, s45, 0
	global_store_dwordx4 v228, v[44:47], s[62:63] sc1
	global_store_dwordx4 v228, v[40:43], s[62:63] offset:64 sc1
	global_store_dwordx4 v228, v[36:39], s[62:63] offset:512 sc1
	global_store_dwordx4 v228, v[32:35], s[62:63] offset:576 sc1
	v_mul_f32_e32 v232, v44, v44
	v_fmac_f32_e32 v232, v45, v45
	v_fmac_f32_e32 v232, v46, v46
	v_fmac_f32_e32 v232, v47, v47
	v_fmac_f32_e32 v232, v40, v40
	v_fmac_f32_e32 v232, v41, v41
	v_fmac_f32_e32 v232, v42, v42
	v_fmac_f32_e32 v232, v43, v43
	v_fmac_f32_e32 v232, v36, v36
	v_fmac_f32_e32 v232, v37, v37
	v_fmac_f32_e32 v232, v38, v38
	v_fmac_f32_e32 v232, v39, v39
	v_fmac_f32_e32 v232, v32, v32
	v_fmac_f32_e32 v232, v33, v33
	v_fmac_f32_e32 v232, v34, v34
	v_fmac_f32_e32 v232, v35, v35
	ds_write_b32 v230, v232 offset:9216
	s_add_u32 s50, s46, 0xb0000
	s_addc_u32 s51, s47, 0
	global_load_dwordx4 v[196:199], v228, s[50:51]
	global_load_dwordx4 v[200:203], v228, s[50:51] offset:64
	global_load_dwordx4 v[204:207], v228, s[50:51] offset:512
	global_load_dwordx4 v[208:211], v228, s[50:51] offset:576
	s_waitcnt vmcnt(8)
	v_pk_fma_f32 v[28:29], v[28:29], v[144:145], v[180:181]
	v_pk_fma_f32 v[30:31], v[30:31], v[146:147], v[182:183]
	v_pk_fma_f32 v[24:25], v[24:25], v[148:149], v[184:185]
	v_pk_fma_f32 v[26:27], v[26:27], v[150:151], v[186:187]
	v_pk_fma_f32 v[12:13], v[12:13], v[152:153], v[188:189]
	v_pk_fma_f32 v[14:15], v[14:15], v[154:155], v[190:191]
	v_pk_fma_f32 v[8:9], v[8:9], v[156:157], v[192:193]
	v_pk_fma_f32 v[10:11], v[10:11], v[158:159], v[194:195]
	s_add_u32 s62, s44, 0xa0000
	s_addc_u32 s63, s45, 0
	global_store_dwordx4 v228, v[28:31], s[62:63] sc1
	global_store_dwordx4 v228, v[24:27], s[62:63] offset:64 sc1
	global_store_dwordx4 v228, v[12:15], s[62:63] offset:512 sc1
	global_store_dwordx4 v228, v[8:11], s[62:63] offset:576 sc1
	v_mul_f32_e32 v232, v28, v28
	v_fmac_f32_e32 v232, v29, v29
	v_fmac_f32_e32 v232, v30, v30
	v_fmac_f32_e32 v232, v31, v31
	v_fmac_f32_e32 v232, v24, v24
	v_fmac_f32_e32 v232, v25, v25
	v_fmac_f32_e32 v232, v26, v26
	v_fmac_f32_e32 v232, v27, v27
	v_fmac_f32_e32 v232, v12, v12
	v_fmac_f32_e32 v232, v13, v13
	v_fmac_f32_e32 v232, v14, v14
	v_fmac_f32_e32 v232, v15, v15
	v_fmac_f32_e32 v232, v8, v8
	v_fmac_f32_e32 v232, v9, v9
	v_fmac_f32_e32 v232, v10, v10
	v_fmac_f32_e32 v232, v11, v11
	ds_write_b32 v230, v232 offset:10240
	s_waitcnt vmcnt(4)
	v_pk_fma_f32 v[20:21], v[20:21], v[144:145], v[196:197]
	v_pk_fma_f32 v[22:23], v[22:23], v[146:147], v[198:199]
	v_pk_fma_f32 v[16:17], v[16:17], v[148:149], v[200:201]
	v_pk_fma_f32 v[18:19], v[18:19], v[150:151], v[202:203]
	v_pk_fma_f32 v[4:5], v[4:5], v[152:153], v[204:205]
	v_pk_fma_f32 v[6:7], v[6:7], v[154:155], v[206:207]
	v_pk_fma_f32 v[0:1], v[0:1], v[156:157], v[208:209]
	v_pk_fma_f32 v[2:3], v[2:3], v[158:159], v[210:211]
	s_add_u32 s62, s44, 0xb0000
	s_addc_u32 s63, s45, 0
	global_store_dwordx4 v228, v[20:23], s[62:63] sc1
	global_store_dwordx4 v228, v[16:19], s[62:63] offset:64 sc1
	global_store_dwordx4 v228, v[4:7], s[62:63] offset:512 sc1
	global_store_dwordx4 v228, v[0:3], s[62:63] offset:576 sc1
	v_mul_f32_e32 v232, v20, v20
	v_fmac_f32_e32 v232, v21, v21
	v_fmac_f32_e32 v232, v22, v22
	v_fmac_f32_e32 v232, v23, v23
	v_fmac_f32_e32 v232, v16, v16
	v_fmac_f32_e32 v232, v17, v17
	v_fmac_f32_e32 v232, v18, v18
	v_fmac_f32_e32 v232, v19, v19
	v_fmac_f32_e32 v232, v4, v4
	v_fmac_f32_e32 v232, v5, v5
	v_fmac_f32_e32 v232, v6, v6
	v_fmac_f32_e32 v232, v7, v7
	v_fmac_f32_e32 v232, v0, v0
	v_fmac_f32_e32 v232, v1, v1
	v_fmac_f32_e32 v232, v2, v2
	v_fmac_f32_e32 v232, v3, v3
	ds_write_b32 v230, v232 offset:11264
	global_load_dwordx4 v[144:147], v229, s[60:61]
	global_load_dwordx4 v[148:151], v229, s[60:61] offset:64
	global_load_dwordx4 v[152:155], v229, s[60:61] offset:512
	global_load_dwordx4 v[156:159], v229, s[60:61] offset:576
	s_waitcnt lgkmcnt(0)
	s_barrier
	v_cmp_gt_u32_e32 vcc, 0x100, v177
	s_and_saveexec_b64 s[0:1], vcc
	s_cbranch_execz .Lf2_nored
	v_lshlrev_b32_e32 v233, 6, v177
	ds_read_b128 v[236:239], v233
	ds_read_b128 v[240:243], v233 offset:16
	ds_read_b128 v[244:247], v233 offset:32
	ds_read_b128 v[248:251], v233 offset:48
	s_lshl_b32 s11, s9, 8
	v_add_u32_e32 v234, s11, v177
	v_lshlrev_b32_e32 v234, 4, v234
	s_lshl_b32 s11, s10, 2
	v_add_u32_e32 v234, s11, v234
	s_waitcnt lgkmcnt(0)
	v_add_f32_e32 v236, v236, v237
	v_add_f32_e32 v236, v236, v238
	v_add_f32_e32 v236, v236, v239
	v_add_f32_e32 v236, v236, v240
	v_add_f32_e32 v236, v236, v241
	v_add_f32_e32 v236, v236, v242
	v_add_f32_e32 v236, v236, v243
	v_add_f32_e32 v236, v236, v244
	v_add_f32_e32 v236, v236, v245
	v_add_f32_e32 v236, v236, v246
	v_add_f32_e32 v236, v236, v247
	v_add_f32_e32 v236, v236, v248
	v_add_f32_e32 v236, v236, v249
	v_add_f32_e32 v236, v236, v250
	v_add_f32_e32 v236, v236, v251
	global_store_dword v234, v236, s[52:53]

.LBB0_1258:
	s_waitcnt vmcnt(0) lgkmcnt(0)
	s_barrier
	v_cmp_eq_u32_e32 vcc, 0, v177
	s_and_saveexec_b64 s[0:1], vcc
	s_cbranch_execz .Lf2_bar_end_b
	s_add_u32 s98, s98, 1
	v_mov_b32_e32 v237, 0x26c00
	ds_read2_b32 v[238:239], v237 offset1:1
	v_mov_b32_e32 v232, s99
	v_mov_b32_e32 v233, 1
	global_atomic_add v234, v232, v233, s[100:101] sc0
	v_add_u32_e32 v232, 0x1000, v232
	v_mov_b32_e32 v240, 0x2480
	s_waitcnt vmcnt(0) lgkmcnt(0)
	v_add_u32_e32 v234, 1, v234
	v_mul_lo_u32 v235, v238, s98
	v_mul_lo_u32 v239, v239, s98
	v_cmp_eq_u32_e32 vcc, v234, v235
	s_and_saveexec_b64 s[4:5], vcc
	s_cbranch_execz .Lf2_skip_b
	buffer_wbl2 sc1
	s_waitcnt vmcnt(0)
	global_atomic_add v240, v233, s[100:101]
	global_atomic_add v240, v233, s[100:101] offset:256
	global_atomic_add v240, v233, s[100:101] offset:512
	global_atomic_add v240, v233, s[100:101] offset:768
	global_atomic_add v240, v233, s[100:101] offset:1024
	global_atomic_add v240, v233, s[100:101] offset:1280
	global_atomic_add v240, v233, s[100:101] offset:1536
	global_atomic_add v240, v233, s[100:101] offset:1792
	global_atomic_add v240, v233, s[100:101] offset:2048
	global_atomic_add v240, v233, s[100:101] offset:2304
	global_atomic_add v240, v233, s[100:101] offset:2560
	global_atomic_add v240, v233, s[100:101] offset:2816
	global_atomic_add v240, v233, s[100:101] offset:3072
	global_atomic_add v240, v233, s[100:101] offset:3328
	global_atomic_add v240, v233, s[100:101] offset:3584
	global_atomic_add v240, v233, s[100:101] offset:3840

.Lf2_bar_end_b:
	s_or_b64 exec, exec, s[0:1]
	s_barrier
	v_lshrrev_b32_e32 v232, 12, v228
	v_lshlrev_b32_e32 v232, 4, v232
	v_add_u32_e32 v233, 0x0, v232
	v_add_u32_e32 v234, 0x100, v232
	v_add_u32_e32 v235, 0x200, v232
	v_add_u32_e32 v236, 0x300, v232
	v_add_u32_e32 v237, 0x800, v232
	v_add_u32_e32 v238, 0x900, v232
	v_add_u32_e32 v239, 0xa00, v232
	v_add_u32_e32 v240, 0xb00, v232
	global_load_dwordx4 v[180:183], v233, s[52:53]
	global_load_dwordx4 v[184:187], v234, s[52:53]
	global_load_dwordx4 v[188:191], v235, s[52:53]
	global_load_dwordx4 v[192:195], v236, s[52:53]
	global_load_dwordx4 v[196:199], v237, s[52:53]
	global_load_dwordx4 v[200:203], v238, s[52:53]
	global_load_dwordx4 v[204:207], v239, s[52:53]
	global_load_dwordx4 v[208:211], v240, s[52:53]
	s_waitcnt vmcnt(0)
	v_mov_b32_e32 v242, 0x3a800000
	v_mov_b32_e32 v243, 0x358637bd
	v_add_f32_e32 v212, v180, v181
	v_add_f32_e32 v212, v212, v182
	v_add_f32_e32 v212, v212, v183
	v_fma_f32 v212, v212, v242, v243
	v_add_f32_e32 v214, v184, v185
	v_add_f32_e32 v214, v214, v186
	v_add_f32_e32 v214, v214, v187
	v_fma_f32 v214, v214, v242, v243
	v_add_f32_e32 v216, v188, v189
	v_add_f32_e32 v216, v216, v190
	v_add_f32_e32 v216, v216, v191
	v_fma_f32 v216, v216, v242, v243
	v_add_f32_e32 v218, v192, v193
	v_add_f32_e32 v218, v218, v194
	v_add_f32_e32 v218, v218, v195
	v_fma_f32 v218, v218, v242, v243
	v_add_f32_e32 v220, v196, v197
	v_add_f32_e32 v220, v220, v198
	v_add_f32_e32 v220, v220, v199
	v_fma_f32 v220, v220, v242, v243
	v_add_f32_e32 v222, v200, v201
	v_add_f32_e32 v222, v222, v202
	v_add_f32_e32 v222, v222, v203
	v_fma_f32 v222, v222, v242, v243
	v_add_f32_e32 v224, v204, v205
	v_add_f32_e32 v224, v224, v206
	v_add_f32_e32 v224, v224, v207
	v_fma_f32 v224, v224, v242, v243
	v_add_f32_e32 v226, v208, v209
	v_add_f32_e32 v226, v226, v210
	v_add_f32_e32 v226, v226, v211
	v_fma_f32 v226, v226, v242, v243
	v_rsq_f32_e32 v212, v212
	v_rsq_f32_e32 v214, v214
	v_rsq_f32_e32 v216, v216
	v_rsq_f32_e32 v218, v218
	v_rsq_f32_e32 v220, v220
	v_rsq_f32_e32 v222, v222
	v_rsq_f32_e32 v224, v224
	v_rsq_f32_e32 v226, v226
	s_nop 0
	s_add_u32 s62, s54, 0x0
	s_addc_u32 s63, s55, 0
	v_pk_mul_f32 v[140:141], v[140:141], v[212:213] op_sel_hi:[1,0]
	v_pk_mul_f32 v[142:143], v[142:143], v[212:213] op_sel_hi:[1,0]
	v_pk_mul_f32 v[140:141], v[160:161], v[140:141]
	v_pk_mul_f32 v[142:143], v[162:163], v[142:143]
	v_pk_fma_f32 v[140:141], v[80:81], v[140:141], v[144:145]
	v_pk_fma_f32 v[142:143], v[82:83], v[142:143], v[146:147]
	v_cvt_pk_bf16_f32 v140, v140, v141
	v_cvt_pk_bf16_f32 v141, v142, v143
	v_pk_mul_f32 v[136:137], v[136:137], v[212:213] op_sel_hi:[1,0]
	v_pk_mul_f32 v[138:139], v[138:139], v[212:213] op_sel_hi:[1,0]
	v_pk_mul_f32 v[136:137], v[164:165], v[136:137]
	v_pk_mul_f32 v[138:139], v[166:167], v[138:139]
	v_pk_fma_f32 v[136:137], v[84:85], v[136:137], v[148:149]
	v_pk_fma_f32 v[138:139], v[86:87], v[138:139], v[150:151]
	v_cvt_pk_bf16_f32 v136, v136, v137
	v_cvt_pk_bf16_f32 v137, v138, v139
	v_pk_mul_f32 v[132:133], v[132:133], v[212:213] op_sel_hi:[1,0]
	v_pk_mul_f32 v[134:135], v[134:135], v[212:213] op_sel_hi:[1,0]
	v_pk_mul_f32 v[132:133], v[168:169], v[132:133]
	v_pk_mul_f32 v[134:135], v[170:171], v[134:135]
	v_pk_fma_f32 v[132:133], v[88:89], v[132:133], v[152:153]
	v_pk_fma_f32 v[134:135], v[90:91], v[134:135], v[154:155]
	v_cvt_pk_bf16_f32 v132, v132, v133
	v_cvt_pk_bf16_f32 v133, v134, v135
	v_pk_mul_f32 v[128:129], v[128:129], v[212:213] op_sel_hi:[1,0]
	v_pk_mul_f32 v[130:131], v[130:131], v[212:213] op_sel_hi:[1,0]
	v_pk_mul_f32 v[128:129], v[172:173], v[128:129]
	v_pk_mul_f32 v[130:131], v[174:175], v[130:131]
	v_pk_fma_f32 v[128:129], v[92:93], v[128:129], v[156:157]
	v_pk_fma_f32 v[130:131], v[94:95], v[130:131], v[158:159]
	v_cvt_pk_bf16_f32 v128, v128, v129
	v_cvt_pk_bf16_f32 v129, v130, v131
	global_store_dwordx2 v231, v[140:141], s[62:63]
	global_store_dwordx2 v231, v[136:137], s[62:63] offset:32
	global_store_dwordx2 v231, v[132:133], s[62:63] offset:256
	global_store_dwordx2 v231, v[128:129], s[62:63] offset:288
	s_add_u32 s62, s54, 0x8000
	s_addc_u32 s63, s55, 0
	v_pk_mul_f32 v[124:125], v[124:125], v[214:215] op_sel_hi:[1,0]
	v_pk_mul_f32 v[126:127], v[126:127], v[214:215] op_sel_hi:[1,0]
	v_pk_mul_f32 v[124:125], v[160:161], v[124:125]
	v_pk_mul_f32 v[126:127], v[162:163], v[126:127]
	v_pk_fma_f32 v[124:125], v[80:81], v[124:125], v[144:145]
	v_pk_fma_f32 v[126:127], v[82:83], v[126:127], v[146:147]
	v_cvt_pk_bf16_f32 v124, v124, v125
	v_cvt_pk_bf16_f32 v125, v126, v127
	v_pk_mul_f32 v[120:121], v[120:121], v[214:215] op_sel_hi:[1,0]
	v_pk_mul_f32 v[122:123], v[122:123], v[214:215] op_sel_hi:[1,0]
	v_pk_mul_f32 v[120:121], v[164:165], v[120:121]
	v_pk_mul_f32 v[122:123], v[166:167], v[122:123]
	v_pk_fma_f32 v[120:121], v[84:85], v[120:121], v[148:149]
	v_pk_fma_f32 v[122:123], v[86:87], v[122:123], v[150:151]
	v_cvt_pk_bf16_f32 v120, v120, v121
	v_cvt_pk_bf16_f32 v121, v122, v123
	v_pk_mul_f32 v[116:117], v[116:117], v[214:215] op_sel_hi:[1,0]
	v_pk_mul_f32 v[118:119], v[118:119], v[214:215] op_sel_hi:[1,0]
	v_pk_mul_f32 v[116:117], v[168:169], v[116:117]
	v_pk_mul_f32 v[118:119], v[170:171], v[118:119]
	v_pk_fma_f32 v[116:117], v[88:89], v[116:117], v[152:153]
	v_pk_fma_f32 v[118:119], v[90:91], v[118:119], v[154:155]
	v_cvt_pk_bf16_f32 v116, v116, v117
	v_cvt_pk_bf16_f32 v117, v118, v119
	v_pk_mul_f32 v[112:113], v[112:113], v[214:215] op_sel_hi:[1,0]
	v_pk_mul_f32 v[114:115], v[114:115], v[214:215] op_sel_hi:[1,0]
	v_pk_mul_f32 v[112:113], v[172:173], v[112:113]
	v_pk_mul_f32 v[114:115], v[174:175], v[114:115]
	v_pk_fma_f32 v[112:113], v[92:93], v[112:113], v[156:157]
	v_pk_fma_f32 v[114:115], v[94:95], v[114:115], v[158:159]
	v_cvt_pk_bf16_f32 v112, v112, v113
	v_cvt_pk_bf16_f32 v113, v114, v115
	global_store_dwordx2 v231, v[124:125], s[62:63]
	global_store_dwordx2 v231, v[120:121], s[62:63] offset:32
	global_store_dwordx2 v231, v[116:117], s[62:63] offset:256
	global_store_dwordx2 v231, v[112:113], s[62:63] offset:288
	s_add_u32 s62, s54, 0x10000
	s_addc_u32 s63, s55, 0
	v_pk_mul_f32 v[108:109], v[108:109], v[216:217] op_sel_hi:[1,0]
	v_pk_mul_f32 v[110:111], v[110:111], v[216:217] op_sel_hi:[1,0]
	v_pk_mul_f32 v[108:109], v[160:161], v[108:109]
	v_pk_mul_f32 v[110:111], v[162:163], v[110:111]
	v_pk_fma_f32 v[108:109], v[80:81], v[108:109], v[144:145]
	v_pk_fma_f32 v[110:111], v[82:83], v[110:111], v[146:147]
	v_cvt_pk_bf16_f32 v108, v108, v109
	v_cvt_pk_bf16_f32 v109, v110, v111
	v_pk_mul_f32 v[104:105], v[104:105], v[216:217] op_sel_hi:[1,0]
	v_pk_mul_f32 v[106:107], v[106:107], v[216:217] op_sel_hi:[1,0]
	v_pk_mul_f32 v[104:105], v[164:165], v[104:105]
	v_pk_mul_f32 v[106:107], v[166:167], v[106:107]
	v_pk_fma_f32 v[104:105], v[84:85], v[104:105], v[148:149]
	v_pk_fma_f32 v[106:107], v[86:87], v[106:107], v[150:151]
	v_cvt_pk_bf16_f32 v104, v104, v105
	v_cvt_pk_bf16_f32 v105, v106, v107
	v_pk_mul_f32 v[100:101], v[100:101], v[216:217] op_sel_hi:[1,0]
	v_pk_mul_f32 v[102:103], v[102:103], v[216:217] op_sel_hi:[1,0]
	v_pk_mul_f32 v[100:101], v[168:169], v[100:101]
	v_pk_mul_f32 v[102:103], v[170:171], v[102:103]
	v_pk_fma_f32 v[100:101], v[88:89], v[100:101], v[152:153]
	v_pk_fma_f32 v[102:103], v[90:91], v[102:103], v[154:155]
	v_cvt_pk_bf16_f32 v100, v100, v101
	v_cvt_pk_bf16_f32 v101, v102, v103
	v_pk_mul_f32 v[96:97], v[96:97], v[216:217] op_sel_hi:[1,0]
	v_pk_mul_f32 v[98:99], v[98:99], v[216:217] op_sel_hi:[1,0]
	v_pk_mul_f32 v[96:97], v[172:173], v[96:97]
	v_pk_mul_f32 v[98:99], v[174:175], v[98:99]
	v_pk_fma_f32 v[96:97], v[92:93], v[96:97], v[156:157]
	v_pk_fma_f32 v[98:99], v[94:95], v[98:99], v[158:159]
	v_cvt_pk_bf16_f32 v96, v96, v97
	v_cvt_pk_bf16_f32 v97, v98, v99
	global_store_dwordx2 v231, v[108:109], s[62:63]
	global_store_dwordx2 v231, v[104:105], s[62:63] offset:32
	global_store_dwordx2 v231, v[100:101], s[62:63] offset:256
	global_store_dwordx2 v231, v[96:97], s[62:63] offset:288
	s_add_u32 s62, s54, 0x18000
	s_addc_u32 s63, s55, 0
	v_pk_mul_f32 v[76:77], v[76:77], v[218:219] op_sel_hi:[1,0]
	v_pk_mul_f32 v[78:79], v[78:79], v[218:219] op_sel_hi:[1,0]
	v_pk_mul_f32 v[76:77], v[160:161], v[76:77]
	v_pk_mul_f32 v[78:79], v[162:163], v[78:79]
	v_pk_fma_f32 v[76:77], v[80:81], v[76:77], v[144:145]
	v_pk_fma_f32 v[78:79], v[82:83], v[78:79], v[146:147]
	v_cvt_pk_bf16_f32 v76, v76, v77
	v_cvt_pk_bf16_f32 v77, v78, v79
	v_pk_mul_f32 v[72:73], v[72:73], v[218:219] op_sel_hi:[1,0]
	v_pk_mul_f32 v[74:75], v[74:75], v[218:219] op_sel_hi:[1,0]
	v_pk_mul_f32 v[72:73], v[164:165], v[72:73]
	v_pk_mul_f32 v[74:75], v[166:167], v[74:75]
	v_pk_fma_f32 v[72:73], v[84:85], v[72:73], v[148:149]
	v_pk_fma_f32 v[74:75], v[86:87], v[74:75], v[150:151]
	v_cvt_pk_bf16_f32 v72, v72, v73
	v_cvt_pk_bf16_f32 v73, v74, v75
	v_pk_mul_f32 v[68:69], v[68:69], v[218:219] op_sel_hi:[1,0]
	v_pk_mul_f32 v[70:71], v[70:71], v[218:219] op_sel_hi:[1,0]
	v_pk_mul_f32 v[68:69], v[168:169], v[68:69]
	v_pk_mul_f32 v[70:71], v[170:171], v[70:71]
	v_pk_fma_f32 v[68:69], v[88:89], v[68:69], v[152:153]
	v_pk_fma_f32 v[70:71], v[90:91], v[70:71], v[154:155]
	v_cvt_pk_bf16_f32 v68, v68, v69
	v_cvt_pk_bf16_f32 v69, v70, v71
	v_pk_mul_f32 v[64:65], v[64:65], v[218:219] op_sel_hi:[1,0]
	v_pk_mul_f32 v[66:67], v[66:67], v[218:219] op_sel_hi:[1,0]
	v_pk_mul_f32 v[64:65], v[172:173], v[64:65]
	v_pk_mul_f32 v[66:67], v[174:175], v[66:67]
	v_pk_fma_f32 v[64:65], v[92:93], v[64:65], v[156:157]
	v_pk_fma_f32 v[66:67], v[94:95], v[66:67], v[158:159]
	v_cvt_pk_bf16_f32 v64, v64, v65
	v_cvt_pk_bf16_f32 v65, v66, v67
	global_store_dwordx2 v231, v[76:77], s[62:63]
	global_store_dwordx2 v231, v[72:73], s[62:63] offset:32
	global_store_dwordx2 v231, v[68:69], s[62:63] offset:256
	global_store_dwordx2 v231, v[64:65], s[62:63] offset:288
	s_add_u32 s62, s54, 0x40000
	s_addc_u32 s63, s55, 0
	v_pk_mul_f32 v[60:61], v[60:61], v[220:221] op_sel_hi:[1,0]
	v_pk_mul_f32 v[62:63], v[62:63], v[220:221] op_sel_hi:[1,0]
	v_pk_mul_f32 v[60:61], v[160:161], v[60:61]
	v_pk_mul_f32 v[62:63], v[162:163], v[62:63]
	v_pk_fma_f32 v[60:61], v[80:81], v[60:61], v[144:145]
	v_pk_fma_f32 v[62:63], v[82:83], v[62:63], v[146:147]
	v_cvt_pk_bf16_f32 v60, v60, v61
	v_cvt_pk_bf16_f32 v61, v62, v63
	v_pk_mul_f32 v[56:57], v[56:57], v[220:221] op_sel_hi:[1,0]
	v_pk_mul_f32 v[58:59], v[58:59], v[220:221] op_sel_hi:[1,0]
	v_pk_mul_f32 v[56:57], v[164:165], v[56:57]
	v_pk_mul_f32 v[58:59], v[166:167], v[58:59]
	v_pk_fma_f32 v[56:57], v[84:85], v[56:57], v[148:149]
	v_pk_fma_f32 v[58:59], v[86:87], v[58:59], v[150:151]
	v_cvt_pk_bf16_f32 v56, v56, v57
	v_cvt_pk_bf16_f32 v57, v58, v59
	v_pk_mul_f32 v[52:53], v[52:53], v[220:221] op_sel_hi:[1,0]
	v_pk_mul_f32 v[54:55], v[54:55], v[220:221] op_sel_hi:[1,0]
	v_pk_mul_f32 v[52:53], v[168:169], v[52:53]
	v_pk_mul_f32 v[54:55], v[170:171], v[54:55]
	v_pk_fma_f32 v[52:53], v[88:89], v[52:53], v[152:153]
	v_pk_fma_f32 v[54:55], v[90:91], v[54:55], v[154:155]
	v_cvt_pk_bf16_f32 v52, v52, v53
	v_cvt_pk_bf16_f32 v53, v54, v55
	v_pk_mul_f32 v[48:49], v[48:49], v[220:221] op_sel_hi:[1,0]
	v_pk_mul_f32 v[50:51], v[50:51], v[220:221] op_sel_hi:[1,0]
	v_pk_mul_f32 v[48:49], v[172:173], v[48:49]
	v_pk_mul_f32 v[50:51], v[174:175], v[50:51]
	v_pk_fma_f32 v[48:49], v[92:93], v[48:49], v[156:157]
	v_pk_fma_f32 v[50:51], v[94:95], v[50:51], v[158:159]
	v_cvt_pk_bf16_f32 v48, v48, v49
	v_cvt_pk_bf16_f32 v49, v50, v51
	global_store_dwordx2 v231, v[60:61], s[62:63]
	global_store_dwordx2 v231, v[56:57], s[62:63] offset:32
	global_store_dwordx2 v231, v[52:53], s[62:63] offset:256
	global_store_dwordx2 v231, v[48:49], s[62:63] offset:288
	s_add_u32 s62, s54, 0x48000
	s_addc_u32 s63, s55, 0
	v_pk_mul_f32 v[44:45], v[44:45], v[222:223] op_sel_hi:[1,0]
	v_pk_mul_f32 v[46:47], v[46:47], v[222:223] op_sel_hi:[1,0]
	v_pk_mul_f32 v[44:45], v[160:161], v[44:45]
	v_pk_mul_f32 v[46:47], v[162:163], v[46:47]
	v_pk_fma_f32 v[44:45], v[80:81], v[44:45], v[144:145]
	v_pk_fma_f32 v[46:47], v[82:83], v[46:47], v[146:147]
	v_cvt_pk_bf16_f32 v44, v44, v45
	v_cvt_pk_bf16_f32 v45, v46, v47
	v_pk_mul_f32 v[40:41], v[40:41], v[222:223] op_sel_hi:[1,0]
	v_pk_mul_f32 v[42:43], v[42:43], v[222:223] op_sel_hi:[1,0]
	v_pk_mul_f32 v[40:41], v[164:165], v[40:41]
	v_pk_mul_f32 v[42:43], v[166:167], v[42:43]
	v_pk_fma_f32 v[40:41], v[84:85], v[40:41], v[148:149]
	v_pk_fma_f32 v[42:43], v[86:87], v[42:43], v[150:151]
	v_cvt_pk_bf16_f32 v40, v40, v41
	v_cvt_pk_bf16_f32 v41, v42, v43
	v_pk_mul_f32 v[36:37], v[36:37], v[222:223] op_sel_hi:[1,0]
	v_pk_mul_f32 v[38:39], v[38:39], v[222:223] op_sel_hi:[1,0]
	v_pk_mul_f32 v[36:37], v[168:169], v[36:37]
	v_pk_mul_f32 v[38:39], v[170:171], v[38:39]
	v_pk_fma_f32 v[36:37], v[88:89], v[36:37], v[152:153]
	v_pk_fma_f32 v[38:39], v[90:91], v[38:39], v[154:155]
	v_cvt_pk_bf16_f32 v36, v36, v37
	v_cvt_pk_bf16_f32 v37, v38, v39
	v_pk_mul_f32 v[32:33], v[32:33], v[222:223] op_sel_hi:[1,0]
	v_pk_mul_f32 v[34:35], v[34:35], v[222:223] op_sel_hi:[1,0]
	v_pk_mul_f32 v[32:33], v[172:173], v[32:33]
	v_pk_mul_f32 v[34:35], v[174:175], v[34:35]
	v_pk_fma_f32 v[32:33], v[92:93], v[32:33], v[156:157]
	v_pk_fma_f32 v[34:35], v[94:95], v[34:35], v[158:159]
	v_cvt_pk_bf16_f32 v32, v32, v33
	v_cvt_pk_bf16_f32 v33, v34, v35
	global_store_dwordx2 v231, v[44:45], s[62:63]
	global_store_dwordx2 v231, v[40:41], s[62:63] offset:32
	global_store_dwordx2 v231, v[36:37], s[62:63] offset:256
	global_store_dwordx2 v231, v[32:33], s[62:63] offset:288
	s_add_u32 s62, s54, 0x50000
	s_addc_u32 s63, s55, 0
	v_pk_mul_f32 v[28:29], v[28:29], v[224:225] op_sel_hi:[1,0]
	v_pk_mul_f32 v[30:31], v[30:31], v[224:225] op_sel_hi:[1,0]
	v_pk_mul_f32 v[28:29], v[160:161], v[28:29]
	v_pk_mul_f32 v[30:31], v[162:163], v[30:31]
	v_pk_fma_f32 v[28:29], v[80:81], v[28:29], v[144:145]
	v_pk_fma_f32 v[30:31], v[82:83], v[30:31], v[146:147]
	v_cvt_pk_bf16_f32 v28, v28, v29
	v_cvt_pk_bf16_f32 v29, v30, v31
	v_pk_mul_f32 v[24:25], v[24:25], v[224:225] op_sel_hi:[1,0]
	v_pk_mul_f32 v[26:27], v[26:27], v[224:225] op_sel_hi:[1,0]
	v_pk_mul_f32 v[24:25], v[164:165], v[24:25]
	v_pk_mul_f32 v[26:27], v[166:167], v[26:27]
	v_pk_fma_f32 v[24:25], v[84:85], v[24:25], v[148:149]
	v_pk_fma_f32 v[26:27], v[86:87], v[26:27], v[150:151]
	v_cvt_pk_bf16_f32 v24, v24, v25
	v_cvt_pk_bf16_f32 v25, v26, v27
	v_pk_mul_f32 v[12:13], v[12:13], v[224:225] op_sel_hi:[1,0]
	v_pk_mul_f32 v[14:15], v[14:15], v[224:225] op_sel_hi:[1,0]
	v_pk_mul_f32 v[12:13], v[168:169], v[12:13]
	v_pk_mul_f32 v[14:15], v[170:171], v[14:15]
	v_pk_fma_f32 v[12:13], v[88:89], v[12:13], v[152:153]
	v_pk_fma_f32 v[14:15], v[90:91], v[14:15], v[154:155]
	v_cvt_pk_bf16_f32 v12, v12, v13
	v_cvt_pk_bf16_f32 v13, v14, v15
	v_pk_mul_f32 v[8:9], v[8:9], v[224:225] op_sel_hi:[1,0]
	v_pk_mul_f32 v[10:11], v[10:11], v[224:225] op_sel_hi:[1,0]
	v_pk_mul_f32 v[8:9], v[172:173], v[8:9]
	v_pk_mul_f32 v[10:11], v[174:175], v[10:11]
	v_pk_fma_f32 v[8:9], v[92:93], v[8:9], v[156:157]
	v_pk_fma_f32 v[10:11], v[94:95], v[10:11], v[158:159]
	v_cvt_pk_bf16_f32 v8, v8, v9
	v_cvt_pk_bf16_f32 v9, v10, v11
	global_store_dwordx2 v231, v[28:29], s[62:63]
	global_store_dwordx2 v231, v[24:25], s[62:63] offset:32
	global_store_dwordx2 v231, v[12:13], s[62:63] offset:256
	global_store_dwordx2 v231, v[8:9], s[62:63] offset:288
	s_add_u32 s62, s54, 0x58000
	s_addc_u32 s63, s55, 0
	v_pk_mul_f32 v[20:21], v[20:21], v[226:227] op_sel_hi:[1,0]
	v_pk_mul_f32 v[22:23], v[22:23], v[226:227] op_sel_hi:[1,0]
	v_pk_mul_f32 v[20:21], v[160:161], v[20:21]
	v_pk_mul_f32 v[22:23], v[162:163], v[22:23]
	v_pk_fma_f32 v[20:21], v[80:81], v[20:21], v[144:145]
	v_pk_fma_f32 v[22:23], v[82:83], v[22:23], v[146:147]
	v_cvt_pk_bf16_f32 v20, v20, v21
	v_cvt_pk_bf16_f32 v21, v22, v23
	v_pk_mul_f32 v[16:17], v[16:17], v[226:227] op_sel_hi:[1,0]
	v_pk_mul_f32 v[18:19], v[18:19], v[226:227] op_sel_hi:[1,0]
	v_pk_mul_f32 v[16:17], v[164:165], v[16:17]
	v_pk_mul_f32 v[18:19], v[166:167], v[18:19]
	v_pk_fma_f32 v[16:17], v[84:85], v[16:17], v[148:149]
	v_pk_fma_f32 v[18:19], v[86:87], v[18:19], v[150:151]
	v_cvt_pk_bf16_f32 v16, v16, v17
	v_cvt_pk_bf16_f32 v17, v18, v19
	v_pk_mul_f32 v[4:5], v[4:5], v[226:227] op_sel_hi:[1,0]
	v_pk_mul_f32 v[6:7], v[6:7], v[226:227] op_sel_hi:[1,0]
	v_pk_mul_f32 v[4:5], v[168:169], v[4:5]
	v_pk_mul_f32 v[6:7], v[170:171], v[6:7]
	v_pk_fma_f32 v[4:5], v[88:89], v[4:5], v[152:153]
	v_pk_fma_f32 v[6:7], v[90:91], v[6:7], v[154:155]
	v_cvt_pk_bf16_f32 v4, v4, v5
	v_cvt_pk_bf16_f32 v5, v6, v7
	v_pk_mul_f32 v[0:1], v[0:1], v[226:227] op_sel_hi:[1,0]
	v_pk_mul_f32 v[2:3], v[2:3], v[226:227] op_sel_hi:[1,0]
	v_pk_mul_f32 v[0:1], v[172:173], v[0:1]
	v_pk_mul_f32 v[2:3], v[174:175], v[2:3]
	v_pk_fma_f32 v[0:1], v[92:93], v[0:1], v[156:157]
	v_pk_fma_f32 v[2:3], v[94:95], v[2:3], v[158:159]
	v_cvt_pk_bf16_f32 v0, v0, v1
	v_cvt_pk_bf16_f32 v1, v2, v3
	global_store_dwordx2 v231, v[20:21], s[62:63]
	global_store_dwordx2 v231, v[16:17], s[62:63] offset:32
	global_store_dwordx2 v231, v[4:5], s[62:63] offset:256
	global_store_dwordx2 v231, v[0:1], s[62:63] offset:288
	v_readlane_b32 s16, v253, 9
	v_readlane_b32 s17, v253, 10
	v_readlane_b32 s34, v254, 63
	v_readlane_b32 s35, v255, 0
	s_waitcnt vmcnt(0)
	s_barrier
	s_and_saveexec_b64 s[0:1], s[34:35]
	s_cbranch_execz .LBB0_1371
	s_add_u32 s98, s98, 1
	v_mov_b32_e32 v7, 0x26c00
	ds_read2_b32 v[8:9], v7 offset1:1
	v_mov_b32_e32 v2, s99
	v_mov_b32_e32 v3, 1
	global_atomic_add v4, v2, v3, s[100:101] sc0
	v_add_u32_e32 v2, 0x1000, v2
	v_mov_b32_e32 v10, 0x2480
	s_waitcnt vmcnt(0) lgkmcnt(0)
	v_add_u32_e32 v4, 1, v4
	v_mul_lo_u32 v5, v8, s98
	v_mul_lo_u32 v9, v9, s98
	v_cmp_eq_u32_e32 vcc, v4, v5
	s_and_saveexec_b64 s[4:5], vcc
	s_cbranch_execz .Lh2_skip_7
	buffer_wbl2 sc1
	s_waitcnt vmcnt(0)
	global_atomic_add v10, v3, s[100:101]
	global_atomic_add v10, v3, s[100:101] offset:256
	global_atomic_add v10, v3, s[100:101] offset:512
	global_atomic_add v10, v3, s[100:101] offset:768
	global_atomic_add v10, v3, s[100:101] offset:1024
	global_atomic_add v10, v3, s[100:101] offset:1280
	global_atomic_add v10, v3, s[100:101] offset:1536
	global_atomic_add v10, v3, s[100:101] offset:1792
	global_atomic_add v10, v3, s[100:101] offset:2048
	global_atomic_add v10, v3, s[100:101] offset:2304
	global_atomic_add v10, v3, s[100:101] offset:2560
	global_atomic_add v10, v3, s[100:101] offset:2816
	global_atomic_add v10, v3, s[100:101] offset:3072
	global_atomic_add v10, v3, s[100:101] offset:3328
	global_atomic_add v10, v3, s[100:101] offset:3584
	global_atomic_add v10, v3, s[100:101] offset:3840
